# on top of v13: m0 save/restore removed around each LDS-DMA in the MLA unit_fixed tile loop (no other m0 user in that phase)
# baseline (speedup 1.0000x reference)
.LBB0_862:
	s_bitcmp1_b32 s53, 0
	s_cselect_b32 s55, 0x6400, 0
	s_and_b32 s97, s96, 0x4000
	v_add_u32_e32 v205, s55, v201
	ds_read_b128 v[82:85], v205
	ds_read_b128 v[206:209], v205 offset:32
	ds_read_b128 v[210:213], v205 offset:12800
	ds_read_b128 v[218:221], v205 offset:64
	ds_read_b128 v[222:225], v205 offset:12832
	ds_read_b128 v[226:229], v205 offset:12864
	v_add_u32_e32 v214, s97, v204
	v_add_u32_e32 v215, 0xc800, v214
	s_and_b64 vcc, exec, s[6:7]
	s_cbranch_vccnz .LBB0_867
	s_cmp_eq_u32 s8, 0x2f40000
	s_cbranch_scc1 .LBB0_866
	s_add_u32 s0, s74, s8
	s_addc_u32 s1, s33, s9
	s_add_u32 s0, s0, 0x35fc0000
	s_addc_u32 s1, s1, 0
	s_sub_i32 s62, 0, s55
	s_add_i32 s63, s62, 0x6400
	s_add_i32 vcc_lo, s63, s54
	v_lshl_add_u64 v[230:231], v[182:183], 1, s[0:1]
	s_mov_b32 m0, vcc_lo
	s_nop 0
	global_load_lds_dwordx4 v[230:231], off
	s_add_i32 vcc_lo, s63, s71
	v_lshl_add_u64 v[230:231], v[184:185], 1, s[0:1]
	s_mov_b32 m0, vcc_lo
	s_nop 0
	global_load_lds_dwordx4 v[230:231], off
	v_lshl_add_u64 v[230:231], v[186:187], 1, s[0:1]
	s_add_i32 s63, s63, s70
	s_mov_b32 m0, s63
	s_nop 0
	global_load_lds_dwordx4 v[230:231], off
	s_and_b64 vcc, exec, s[2:3]
	s_cbranch_vccnz .LBB0_866
	s_add_i32 s62, s62, 0xc400
	v_lshl_add_u64 v[230:231], v[188:189], 1, s[0:1]
	s_mov_b32 m0, s62
	s_nop 0
	global_load_lds_dwordx4 v[230:231], off
.LBB0_866:
	s_sub_i32 s0, 0, s97
	s_add_i32 s0, s0, 0x10800
	v_lshl_add_u64 v[230:231], v[190:191], 1, s[76:77]
	s_add_i32 s1, s0, s54
	s_mov_b32 m0, s1
	s_nop 0
	global_load_lds_dwordx4 v[230:231], off
	v_lshl_add_u64 v[230:231], v[192:193], 1, s[76:77]
	s_add_i32 s0, s0, s71
	s_mov_b32 m0, s0
	s_nop 0
	global_load_lds_dwordx4 v[230:231], off
.LBB0_867:
	s_waitcnt lgkmcnt(5)
	v_mfma_f32_32x32x16_bf16 v[98:113], v[82:85], v[114:117], v[66:81]
	s_waitcnt lgkmcnt(3)
	v_mfma_f32_32x32x16_bf16 v[82:97], v[210:213], v[114:117], v[66:81]
	ds_read_b128 v[210:213], v205 offset:96
	ds_read_b128 v[230:233], v205 offset:12896
	v_mfma_f32_32x32x16_bf16 v[98:113], v[206:209], v[118:121], v[98:113]
	s_waitcnt lgkmcnt(3)
	v_mfma_f32_32x32x16_bf16 v[82:97], v[222:225], v[118:121], v[82:97]
	ds_read_b128 v[206:209], v205 offset:128
	ds_read_b128 v[222:225], v205 offset:12928
	v_mfma_f32_32x32x16_bf16 v[98:113], v[218:221], v[122:125], v[98:113]
	s_waitcnt lgkmcnt(4)
	v_mfma_f32_32x32x16_bf16 v[82:97], v[226:229], v[122:125], v[82:97]
	ds_read_b128 v[218:221], v205 offset:160
	ds_read_b128 v[226:229], v205 offset:12960
	s_waitcnt lgkmcnt(5)
	v_mfma_f32_32x32x16_bf16 v[98:113], v[210:213], v[126:129], v[98:113]
	s_waitcnt lgkmcnt(4)
	v_mfma_f32_32x32x16_bf16 v[82:97], v[230:233], v[126:129], v[82:97]
	ds_read_b128 v[210:213], v205 offset:192
	ds_read_b128 v[230:233], v205 offset:12992
	s_waitcnt lgkmcnt(5)
	v_mfma_f32_32x32x16_bf16 v[98:113], v[206:209], v[130:133], v[98:113]
	s_waitcnt lgkmcnt(4)
	v_mfma_f32_32x32x16_bf16 v[82:97], v[222:225], v[130:133], v[82:97]
	ds_read_b128 v[206:209], v205 offset:224
	ds_read_b128 v[222:225], v205 offset:13024
	s_waitcnt lgkmcnt(5)
	v_mfma_f32_32x32x16_bf16 v[98:113], v[218:221], v[134:137], v[98:113]
	s_waitcnt lgkmcnt(4)
	v_mfma_f32_32x32x16_bf16 v[82:97], v[226:229], v[134:137], v[82:97]
	ds_read_b128 v[218:221], v205 offset:256
	ds_read_b128 v[226:229], v205 offset:13056
	s_waitcnt lgkmcnt(5)
	v_mfma_f32_32x32x16_bf16 v[98:113], v[210:213], v[138:141], v[98:113]
	s_waitcnt lgkmcnt(4)
	v_mfma_f32_32x32x16_bf16 v[82:97], v[230:233], v[138:141], v[82:97]
	ds_read_b128 v[210:213], v205 offset:288
	ds_read_b128 v[230:233], v205 offset:13088
	ds_read_b64_tr_b16 v[234:235], v214 offset:51200
	ds_read_b64_tr_b16 v[236:237], v214 offset:53248
	s_waitcnt lgkmcnt(7)
	v_mfma_f32_32x32x16_bf16 v[98:113], v[206:209], v[142:145], v[98:113]
	s_waitcnt lgkmcnt(6)
	v_mfma_f32_32x32x16_bf16 v[82:97], v[222:225], v[142:145], v[82:97]
	ds_read_b128 v[206:209], v205 offset:320
	ds_read_b128 v[222:225], v205 offset:13120
	ds_read_b64_tr_b16 v[238:239], v214 offset:55296
	ds_read_b64_tr_b16 v[240:241], v214 offset:57344
	s_waitcnt lgkmcnt(9)
	v_mfma_f32_32x32x16_bf16 v[98:113], v[218:221], v[146:149], v[98:113]
	s_waitcnt lgkmcnt(8)
	v_mfma_f32_32x32x16_bf16 v[82:97], v[226:229], v[146:149], v[82:97]
	ds_read_b128 v[218:221], v205 offset:352
	ds_read_b128 v[226:229], v205 offset:13152
	ds_read_b64_tr_b16 v[242:243], v214 offset:59392
	ds_read_b64_tr_b16 v[244:245], v214 offset:61440
	s_waitcnt lgkmcnt(11)
	v_mfma_f32_32x32x16_bf16 v[98:113], v[210:213], v[154:157], v[98:113]
	s_waitcnt lgkmcnt(10)
	v_mfma_f32_32x32x16_bf16 v[82:97], v[230:233], v[154:157], v[82:97]
	ds_read_b64_tr_b16 v[210:211], v214 offset:63488
	ds_read_b64_tr_b16 v[212:213], v215 offset:14336
	s_waitcnt lgkmcnt(9)
	v_mfma_f32_32x32x16_bf16 v[98:113], v[206:209], v[150:153], v[98:113]
	s_waitcnt lgkmcnt(8)
	v_mfma_f32_32x32x16_bf16 v[82:97], v[222:225], v[150:153], v[82:97]
	ds_read_b64_tr_b16 v[206:207], v214 offset:51712
	ds_read_b64_tr_b16 v[208:209], v214 offset:53760
	s_waitcnt lgkmcnt(7)
	v_mfma_f32_32x32x16_bf16 v[98:113], v[218:221], v[158:161], v[98:113]
	s_waitcnt lgkmcnt(6)
	v_mfma_f32_32x32x16_bf16 v[82:97], v[226:229], v[158:161], v[82:97]
	ds_read_b64_tr_b16 v[218:219], v214 offset:55808
	ds_read_b64_tr_b16 v[220:221], v214 offset:57856
	v_mfma_f32_32x32x16_bf16 v[50:65], v[162:165], v[234:237], v[50:65]
	ds_read_b64_tr_b16 v[222:223], v214 offset:59904
	ds_read_b64_tr_b16 v[224:225], v214 offset:61952
	v_mfma_f32_32x32x16_bf16 v[50:65], v[166:169], v[238:241], v[50:65]
	ds_read_b64_tr_b16 v[226:227], v214 offset:64000
	ds_read_b64_tr_b16 v[228:229], v215 offset:14848
	s_waitcnt lgkmcnt(10)
	v_mfma_f32_32x32x16_bf16 v[50:65], v[170:173], v[242:245], v[50:65]
	ds_read_b64_tr_b16 v[230:231], v214 offset:52224
	ds_read_b64_tr_b16 v[232:233], v214 offset:54272
	s_waitcnt lgkmcnt(10)
	v_mfma_f32_32x32x16_bf16 v[50:65], v[174:177], v[210:213], v[50:65]
	ds_read_b64_tr_b16 v[210:211], v214 offset:56320
	ds_read_b64_tr_b16 v[212:213], v214 offset:58368
	s_waitcnt lgkmcnt(10)
	v_mfma_f32_32x32x16_bf16 v[34:49], v[162:165], v[206:209], v[34:49]
	ds_read_b64_tr_b16 v[206:207], v214 offset:60416
	ds_read_b64_tr_b16 v[208:209], v214 offset:62464
	s_waitcnt lgkmcnt(10)
	v_mfma_f32_32x32x16_bf16 v[34:49], v[166:169], v[218:221], v[34:49]
	ds_read_b64_tr_b16 v[218:219], v214 offset:64512
	ds_read_b64_tr_b16 v[220:221], v215 offset:15360
	s_waitcnt lgkmcnt(10)
	v_mfma_f32_32x32x16_bf16 v[34:49], v[170:173], v[222:225], v[34:49]
	ds_read_b64_tr_b16 v[222:223], v214 offset:52736
	ds_read_b64_tr_b16 v[224:225], v214 offset:54784
	s_waitcnt lgkmcnt(10)
	v_mfma_f32_32x32x16_bf16 v[34:49], v[174:177], v[226:229], v[34:49]
	ds_read_b64_tr_b16 v[226:227], v214 offset:56832
	ds_read_b64_tr_b16 v[228:229], v214 offset:58880
	s_waitcnt lgkmcnt(10)
	v_mfma_f32_32x32x16_bf16 v[18:33], v[162:165], v[230:233], v[18:33]
	ds_read_b64_tr_b16 v[230:231], v214 offset:60928
	ds_read_b64_tr_b16 v[232:233], v214 offset:62976
	s_waitcnt lgkmcnt(10)
	v_mfma_f32_32x32x16_bf16 v[18:33], v[166:169], v[210:213], v[18:33]
	ds_read_b64_tr_b16 v[210:211], v214 offset:65024
	ds_read_b64_tr_b16 v[212:213], v215 offset:15872
	s_waitcnt lgkmcnt(10)
	v_mfma_f32_32x32x16_bf16 v[18:33], v[170:173], v[206:209], v[18:33]
	s_waitcnt lgkmcnt(8)
	v_mfma_f32_32x32x16_bf16 v[18:33], v[174:177], v[218:221], v[18:33]
	s_waitcnt lgkmcnt(6)
	v_mfma_f32_32x32x16_bf16 v[2:17], v[162:165], v[222:225], v[2:17]
	s_waitcnt lgkmcnt(4)
	v_mfma_f32_32x32x16_bf16 v[2:17], v[166:169], v[226:229], v[2:17]
	s_waitcnt lgkmcnt(2)
	v_mfma_f32_32x32x16_bf16 v[2:17], v[170:173], v[230:233], v[2:17]
	s_waitcnt lgkmcnt(0)
	v_mfma_f32_32x32x16_bf16 v[2:17], v[174:177], v[210:213], v[2:17]
	s_and_b64 vcc, exec, s[4:5]
	s_cbranch_vccnz .LBB0_872
	s_waitcnt vmcnt(0) lgkmcnt(0)
	s_barrier
	s_cmpk_gt_u32 s53, 0x7d
	s_cbranch_scc1 .LBB0_870
	s_add_u32 s0, s74, s8
	s_addc_u32 s1, s33, s9
	s_add_u32 s0, s0, 0x36020000
	s_addc_u32 s1, s1, 0
	s_add_i32 s55, s55, 0
	v_lshl_add_u64 v[162:163], v[182:183], 1, s[0:1]
	s_add_i32 s62, s55, s54
	s_mov_b32 m0, s62
	s_nop 0
	global_load_lds_dwordx4 v[162:163], off
	v_lshl_add_u64 v[162:163], v[184:185], 1, s[0:1]
	s_add_i32 s62, s55, s71
	s_mov_b32 m0, s62
	s_nop 0
	global_load_lds_dwordx4 v[162:163], off
	v_lshl_add_u64 v[162:163], v[186:187], 1, s[0:1]
	s_add_i32 s55, s55, s70
	s_mov_b32 m0, s55
	s_nop 0
	global_load_lds_dwordx4 v[162:163], off
.LBB0_870:
	s_cmp_eq_u32 s8, 0x2f40000
	s_cbranch_scc1 .LBB0_872
	s_add_u32 s0, s76, 0x80000
	s_addc_u32 s1, s77, 0
	s_add_i32 s55, s97, 0
	s_add_i32 s55, s55, 0xc800
	v_lshl_add_u64 v[162:163], v[190:191], 1, s[0:1]
	s_add_i32 s62, s55, s54
	v_lshl_add_u64 v[164:165], v[192:193], 1, s[0:1]
	s_mov_b32 m0, s62
	s_nop 0
	global_load_lds_dwordx4 v[162:163], off
	s_add_i32 s55, s55, s71
	s_mov_b32 m0, s55
	s_nop 0
	global_load_lds_dwordx4 v[164:165], off

.LBB0_2806:
	s_bitcmp1_b32 s82, 0
	s_cselect_b32 s86, 0x6400, 0
	s_and_b32 s85, s84, 0x4000
	v_add_u32_e32 v205, s86, v201
	ds_read_b128 v[82:85], v205
	ds_read_b128 v[206:209], v205 offset:32
	ds_read_b128 v[210:213], v205 offset:12800
	ds_read_b128 v[218:221], v205 offset:64
	ds_read_b128 v[222:225], v205 offset:12832
	ds_read_b128 v[226:229], v205 offset:12864
	v_add_u32_e32 v214, s85, v204
	v_add_u32_e32 v215, 0xc800, v214
	s_and_b64 vcc, exec, s[6:7]
	s_cbranch_vccnz .LBB0_2811
	s_cmp_eq_u32 s8, 0x2f40000
	s_cbranch_scc1 .LBB0_2810
	s_add_u32 s0, s33, s8
	s_addc_u32 s1, s78, s9
	s_add_u32 s0, s0, 0x35fc0000
	s_addc_u32 s1, s1, 0
	s_sub_i32 s62, 0, s86
	s_add_i32 s63, s62, 0x6400
	v_lshl_add_u64 v[230:231], v[182:183], 1, s[0:1]
	s_add_i32 s66, s63, s70
	s_mov_b32 m0, s66
	s_nop 0
	global_load_lds_dwordx4 v[230:231], off
	v_lshl_add_u64 v[230:231], v[184:185], 1, s[0:1]
	s_add_i32 s66, s63, s71
	s_mov_b32 m0, s66
	s_nop 0
	global_load_lds_dwordx4 v[230:231], off
	v_lshl_add_u64 v[230:231], v[186:187], 1, s[0:1]
	s_add_i32 s63, s63, s83
	s_mov_b32 m0, s63
	s_nop 0
	global_load_lds_dwordx4 v[230:231], off
	s_and_b64 vcc, exec, s[2:3]
	s_cbranch_vccnz .LBB0_2810
	s_add_i32 s62, s62, 0xc400
	v_lshl_add_u64 v[230:231], v[188:189], 1, s[0:1]
	s_mov_b32 m0, s62
	s_nop 0
	global_load_lds_dwordx4 v[230:231], off
.LBB0_2810:
	s_sub_i32 s0, 0, s85
	s_add_i32 s0, s0, 0x10800
	v_lshl_add_u64 v[230:231], v[190:191], 1, s[76:77]
	s_add_i32 s1, s0, s70
	s_mov_b32 m0, s1
	s_nop 0
	global_load_lds_dwordx4 v[230:231], off
	v_lshl_add_u64 v[230:231], v[192:193], 1, s[76:77]
	s_add_i32 s0, s0, s71
	s_mov_b32 m0, s0
	s_nop 0
	global_load_lds_dwordx4 v[230:231], off
.LBB0_2811:
	s_waitcnt lgkmcnt(5)
	v_mfma_f32_32x32x16_bf16 v[98:113], v[82:85], v[114:117], v[66:81]
	s_waitcnt lgkmcnt(3)
	v_mfma_f32_32x32x16_bf16 v[82:97], v[210:213], v[114:117], v[66:81]
	ds_read_b128 v[210:213], v205 offset:96
	ds_read_b128 v[230:233], v205 offset:12896
	v_mfma_f32_32x32x16_bf16 v[98:113], v[206:209], v[118:121], v[98:113]
	s_waitcnt lgkmcnt(3)
	v_mfma_f32_32x32x16_bf16 v[82:97], v[222:225], v[118:121], v[82:97]
	ds_read_b128 v[206:209], v205 offset:128
	ds_read_b128 v[222:225], v205 offset:12928
	v_mfma_f32_32x32x16_bf16 v[98:113], v[218:221], v[122:125], v[98:113]
	s_waitcnt lgkmcnt(4)
	v_mfma_f32_32x32x16_bf16 v[82:97], v[226:229], v[122:125], v[82:97]
	ds_read_b128 v[218:221], v205 offset:160
	ds_read_b128 v[226:229], v205 offset:12960
	s_waitcnt lgkmcnt(5)
	v_mfma_f32_32x32x16_bf16 v[98:113], v[210:213], v[126:129], v[98:113]
	s_waitcnt lgkmcnt(4)
	v_mfma_f32_32x32x16_bf16 v[82:97], v[230:233], v[126:129], v[82:97]
	ds_read_b128 v[210:213], v205 offset:192
	ds_read_b128 v[230:233], v205 offset:12992
	s_waitcnt lgkmcnt(5)
	v_mfma_f32_32x32x16_bf16 v[98:113], v[206:209], v[130:133], v[98:113]
	s_waitcnt lgkmcnt(4)
	v_mfma_f32_32x32x16_bf16 v[82:97], v[222:225], v[130:133], v[82:97]
	ds_read_b128 v[206:209], v205 offset:224
	ds_read_b128 v[222:225], v205 offset:13024
	s_waitcnt lgkmcnt(5)
	v_mfma_f32_32x32x16_bf16 v[98:113], v[218:221], v[134:137], v[98:113]
	s_waitcnt lgkmcnt(4)
	v_mfma_f32_32x32x16_bf16 v[82:97], v[226:229], v[134:137], v[82:97]
	ds_read_b128 v[218:221], v205 offset:256
	ds_read_b128 v[226:229], v205 offset:13056
	s_waitcnt lgkmcnt(5)
	v_mfma_f32_32x32x16_bf16 v[98:113], v[210:213], v[138:141], v[98:113]
	s_waitcnt lgkmcnt(4)
	v_mfma_f32_32x32x16_bf16 v[82:97], v[230:233], v[138:141], v[82:97]
	ds_read_b128 v[210:213], v205 offset:288
	ds_read_b128 v[230:233], v205 offset:13088
	ds_read_b64_tr_b16 v[234:235], v214 offset:51200
	ds_read_b64_tr_b16 v[236:237], v214 offset:53248
	s_waitcnt lgkmcnt(7)
	v_mfma_f32_32x32x16_bf16 v[98:113], v[206:209], v[142:145], v[98:113]
	s_waitcnt lgkmcnt(6)
	v_mfma_f32_32x32x16_bf16 v[82:97], v[222:225], v[142:145], v[82:97]
	ds_read_b128 v[206:209], v205 offset:320
	ds_read_b128 v[222:225], v205 offset:13120
	ds_read_b64_tr_b16 v[238:239], v214 offset:55296
	ds_read_b64_tr_b16 v[240:241], v214 offset:57344
	s_waitcnt lgkmcnt(9)
	v_mfma_f32_32x32x16_bf16 v[98:113], v[218:221], v[146:149], v[98:113]
	s_waitcnt lgkmcnt(8)
	v_mfma_f32_32x32x16_bf16 v[82:97], v[226:229], v[146:149], v[82:97]
	ds_read_b128 v[218:221], v205 offset:352
	ds_read_b128 v[226:229], v205 offset:13152
	ds_read_b64_tr_b16 v[242:243], v214 offset:59392
	ds_read_b64_tr_b16 v[244:245], v214 offset:61440
	s_waitcnt lgkmcnt(11)
	v_mfma_f32_32x32x16_bf16 v[98:113], v[210:213], v[154:157], v[98:113]
	s_waitcnt lgkmcnt(10)
	v_mfma_f32_32x32x16_bf16 v[82:97], v[230:233], v[154:157], v[82:97]
	ds_read_b64_tr_b16 v[210:211], v214 offset:63488
	ds_read_b64_tr_b16 v[212:213], v215 offset:14336
	s_waitcnt lgkmcnt(9)
	v_mfma_f32_32x32x16_bf16 v[98:113], v[206:209], v[150:153], v[98:113]
	s_waitcnt lgkmcnt(8)
	v_mfma_f32_32x32x16_bf16 v[82:97], v[222:225], v[150:153], v[82:97]
	ds_read_b64_tr_b16 v[206:207], v214 offset:51712
	ds_read_b64_tr_b16 v[208:209], v214 offset:53760
	s_waitcnt lgkmcnt(7)
	v_mfma_f32_32x32x16_bf16 v[98:113], v[218:221], v[158:161], v[98:113]
	s_waitcnt lgkmcnt(6)
	v_mfma_f32_32x32x16_bf16 v[82:97], v[226:229], v[158:161], v[82:97]
	ds_read_b64_tr_b16 v[218:219], v214 offset:55808
	ds_read_b64_tr_b16 v[220:221], v214 offset:57856
	v_mfma_f32_32x32x16_bf16 v[50:65], v[162:165], v[234:237], v[50:65]
	ds_read_b64_tr_b16 v[222:223], v214 offset:59904
	ds_read_b64_tr_b16 v[224:225], v214 offset:61952
	v_mfma_f32_32x32x16_bf16 v[50:65], v[166:169], v[238:241], v[50:65]
	ds_read_b64_tr_b16 v[226:227], v214 offset:64000
	ds_read_b64_tr_b16 v[228:229], v215 offset:14848
	s_waitcnt lgkmcnt(10)
	v_mfma_f32_32x32x16_bf16 v[50:65], v[170:173], v[242:245], v[50:65]
	ds_read_b64_tr_b16 v[230:231], v214 offset:52224
	ds_read_b64_tr_b16 v[232:233], v214 offset:54272
	s_waitcnt lgkmcnt(10)
	v_mfma_f32_32x32x16_bf16 v[50:65], v[174:177], v[210:213], v[50:65]
	ds_read_b64_tr_b16 v[210:211], v214 offset:56320
	ds_read_b64_tr_b16 v[212:213], v214 offset:58368
	s_waitcnt lgkmcnt(10)
	v_mfma_f32_32x32x16_bf16 v[34:49], v[162:165], v[206:209], v[34:49]
	ds_read_b64_tr_b16 v[206:207], v214 offset:60416
	ds_read_b64_tr_b16 v[208:209], v214 offset:62464
	s_waitcnt lgkmcnt(10)
	v_mfma_f32_32x32x16_bf16 v[34:49], v[166:169], v[218:221], v[34:49]
	ds_read_b64_tr_b16 v[218:219], v214 offset:64512
	ds_read_b64_tr_b16 v[220:221], v215 offset:15360
	s_waitcnt lgkmcnt(10)
	v_mfma_f32_32x32x16_bf16 v[34:49], v[170:173], v[222:225], v[34:49]
	ds_read_b64_tr_b16 v[222:223], v214 offset:52736
	ds_read_b64_tr_b16 v[224:225], v214 offset:54784
	s_waitcnt lgkmcnt(10)
	v_mfma_f32_32x32x16_bf16 v[34:49], v[174:177], v[226:229], v[34:49]
	ds_read_b64_tr_b16 v[226:227], v214 offset:56832
	ds_read_b64_tr_b16 v[228:229], v214 offset:58880
	s_waitcnt lgkmcnt(10)
	v_mfma_f32_32x32x16_bf16 v[18:33], v[162:165], v[230:233], v[18:33]
	ds_read_b64_tr_b16 v[230:231], v214 offset:60928
	ds_read_b64_tr_b16 v[232:233], v214 offset:62976
	s_waitcnt lgkmcnt(10)
	v_mfma_f32_32x32x16_bf16 v[18:33], v[166:169], v[210:213], v[18:33]
	ds_read_b64_tr_b16 v[210:211], v214 offset:65024
	ds_read_b64_tr_b16 v[212:213], v215 offset:15872
	s_waitcnt lgkmcnt(10)
	v_mfma_f32_32x32x16_bf16 v[18:33], v[170:173], v[206:209], v[18:33]
	s_waitcnt lgkmcnt(8)
	v_mfma_f32_32x32x16_bf16 v[18:33], v[174:177], v[218:221], v[18:33]
	s_waitcnt lgkmcnt(6)
	v_mfma_f32_32x32x16_bf16 v[2:17], v[162:165], v[222:225], v[2:17]
	s_waitcnt lgkmcnt(4)
	v_mfma_f32_32x32x16_bf16 v[2:17], v[166:169], v[226:229], v[2:17]
	s_waitcnt lgkmcnt(2)
	v_mfma_f32_32x32x16_bf16 v[2:17], v[170:173], v[230:233], v[2:17]
	s_waitcnt lgkmcnt(0)
	v_mfma_f32_32x32x16_bf16 v[2:17], v[174:177], v[210:213], v[2:17]
	s_and_b64 vcc, exec, s[4:5]
	s_cbranch_vccnz .LBB0_2816
	s_waitcnt vmcnt(0) lgkmcnt(0)
	s_barrier
	s_cmpk_gt_u32 s82, 0x7d
	s_cbranch_scc1 .LBB0_2814
	s_add_u32 s0, s33, s8
	s_addc_u32 s1, s78, s9
	s_add_u32 s0, s0, 0x36020000
	s_addc_u32 s1, s1, 0
	s_add_i32 s62, s86, 0
	v_lshl_add_u64 v[162:163], v[182:183], 1, s[0:1]
	s_add_i32 s63, s62, s70
	s_mov_b32 m0, s63
	s_nop 0
	global_load_lds_dwordx4 v[162:163], off
	v_lshl_add_u64 v[162:163], v[184:185], 1, s[0:1]
	s_add_i32 s63, s62, s71
	s_mov_b32 m0, s63
	s_nop 0
	global_load_lds_dwordx4 v[162:163], off
	v_lshl_add_u64 v[162:163], v[186:187], 1, s[0:1]
	s_add_i32 s62, s62, s83
	s_mov_b32 m0, s62
	s_nop 0
	global_load_lds_dwordx4 v[162:163], off
.LBB0_2814:
	s_cmp_eq_u32 s8, 0x2f40000
	s_cbranch_scc1 .LBB0_2816
	s_add_u32 s0, s76, 0x80000
	s_addc_u32 s1, s77, 0
	s_add_i32 s62, s85, 0
	s_add_i32 s62, s62, 0xc800
	v_lshl_add_u64 v[162:163], v[190:191], 1, s[0:1]
	s_add_i32 s63, s62, s70
	v_lshl_add_u64 v[164:165], v[192:193], 1, s[0:1]
	s_mov_b32 m0, s63
	s_nop 0
	global_load_lds_dwordx4 v[162:163], off
	s_add_i32 s62, s62, s71
	s_mov_b32 m0, s62
	s_nop 0
	global_load_lds_dwordx4 v[164:165], off
